# N18+DKT with a grid-size guard on the DK tail remap (falls back to the original round-robin when NGW != 2048)
# baseline (speedup 1.0000x reference)
; __device__ __forceinline__ void dk_phase(const Frame& F, const bf16* QKrm, const unsigned char* KT, const unsigned char* VT, const float* BG, unsigned char* ITEMS) {
;     ...
;     for (int it = F.gw; it < NCB * 64; it += F.NGW) {
;         int lane_l = F.lane; asm volatile("" : "+v"(lane_l));
;         const int lane = lane_l, r32 = lane & 31, hi = lane >> 5;
;         const int cb = it >> 6, hv = (it >> 1) & 31, dir = it & 1, hk = hv >> 1;
;         unsigned char* item = ITEMS + (size_t)it * ITEM_BYTES;
.Ldk_tail:
	s_cmpk_eq_u32 s64, 0x800
	s_cbranch_scc1 .Ldk_t2
	s_cmpk_lt_i32 s52, 0x4100
	s_cbranch_scc1 .LBB0_461
	s_branch .LBB0_595
